# MLA loop: LDS-DMA issue for tile t+3 moved from the loop head to behind the first QK fragment reads (LDS read latency covers the DMA issue)
# speedup vs baseline: 1.0074x; 1.0074x over previous
.LBB0_562:
	s_waitcnt vmcnt(7)
	s_barrier
.LBB0_564:
	s_mul_hi_u32 s7, s4, 0xaaaaaaab
	s_lshr_b32 s7, s7, 1
	s_mul_i32 s7, s7, 0x9000
	v_subrev_u32_e32 v64, s7, v166
	v_add_u32_e32 v200, s36, v175
	v_add_u32_e32 v201, v200, v64
	v_subrev_u32_e32 v202, s7, v172
	v_subrev_u32_e32 v203, s7, v173
	v_subrev_u32_e32 v204, s7, v174
	v_add_u32_e32 v202, v200, v202
	v_add_u32_e32 v203, v200, v203
	v_add_u32_e32 v204, v200, v204
	ds_read_b128 v[64:67], v201 offset:12288
	ds_read_b128 v[232:235], v202 offset:12288
	ds_read_b128 v[236:239], v203 offset:12288
	ds_read_b128 v[240:243], v204 offset:12288
	ds_read_b128 v[244:247], v201 offset:12416
	ds_read_b128 v[248:251], v202 offset:12416
	ds_read_b128 v[252:255], v203 offset:12416
	s_add_i32 s7, s6, -3
	s_cmpk_gt_u32 s7, 0x84
	s_cbranch_scc1 .Lmy_mla_nodma_a
	s_and_b32 s7, s6, 0xff
	s_mulk_i32 s7, 0xab
	s_lshr_b32 s7, s7, 9
	s_mul_i32 s7, s7, 3
	s_sub_i32 s7, s6, s7
	s_and_b32 s7, s7, 0xff
	s_mulk_i32 s7, 0x3000
	v_readfirstlane_b32 s100, v167
	s_and_b32 s101, s5, 0x6000
	s_add_i32 s7, s7, s100
	s_add_i32 s101, s101, s100
	s_add_i32 m0, s7, 0x0
	v_lshl_add_u64 v[198:199], v[150:151], 0, s[20:21]
	global_load_lds_dwordx4 v[156:157], off
	s_add_i32 m0, s7, 0x1000
	s_nop 0
	global_load_lds_dwordx4 v[154:155], off
	s_add_i32 m0, s7, 0x2000
	s_nop 0
	global_load_lds_dwordx4 v[152:153], off
	s_add_i32 m0, s101, 0x9000
	s_nop 0
	global_load_lds_dwordx4 v[150:151], off
	s_add_i32 m0, s101, 0xa000
	s_nop 0
	global_load_lds_dwordx4 v[198:199], off
.Lmy_mla_nodma_a:
	s_add_i32 s7, s5, 0xffffa000
	s_and_b32 s7, s7, 0x6000
	s_add_i32 s7, s7, 16
	s_waitcnt lgkmcnt(6)
	v_mfma_f32_32x32x16_bf16 v[64:79], v[64:67], v[142:145], 0
	v_max_f32_e32 v177, v80, v80
	v_max_f32_e32 v176, v81, v81
	v_max_f32_e32 v176, v177, v176
	v_max3_f32 v176, v176, v82, v83
	v_max3_f32 v176, v176, v84, v85
	v_max3_f32 v176, v176, v86, v87
	s_waitcnt lgkmcnt(5)
	v_mfma_f32_32x32x16_bf16 v[64:79], v[232:235], v[138:141], v[64:79]
	ds_read_b128 v[232:235], v204 offset:12416
	v_max3_f32 v176, v176, v88, v89
	v_max3_f32 v176, v176, v90, v91
	v_max3_f32 v176, v176, v92, v93
	v_max3_f32 v176, v176, v94, v95
	v_mov_b32_e32 v177, v176
	s_waitcnt lgkmcnt(5)
	v_mfma_f32_32x32x16_bf16 v[64:79], v[236:239], v[134:137], v[64:79]
	ds_read_b128 v[236:239], v201 offset:12544
	v_permlane32_swap_b32_e32 v176, v177
	v_max_f32_e32 v177, v177, v177
	v_max_f32_e32 v176, v176, v176
	v_max_f32_e32 v176, v176, v177
	v_add_f32_e32 v177, 0x41000000, v165
	v_cmp_gt_f32_e32 vcc, v176, v177
	s_cbranch_vccz .LBB0_566
	v_max_f32_e32 v176, v176, v176
	v_max_f32_e32 v177, v165, v165
	v_max_f32_e32 v177, v177, v176
	v_sub_f32_e32 v165, v165, v177
	v_exp_f32_e32 v176, v165
	v_mov_b32_e32 v165, v177
	v_pk_mul_f32 v[62:63], v[62:63], v[176:177] op_sel_hi:[1,0]
	v_pk_mul_f32 v[60:61], v[60:61], v[176:177] op_sel_hi:[1,0]
	v_pk_mul_f32 v[58:59], v[58:59], v[176:177] op_sel_hi:[1,0]
	v_pk_mul_f32 v[56:57], v[56:57], v[176:177] op_sel_hi:[1,0]
	v_pk_mul_f32 v[54:55], v[54:55], v[176:177] op_sel_hi:[1,0]
	v_pk_mul_f32 v[52:53], v[52:53], v[176:177] op_sel_hi:[1,0]
	v_pk_mul_f32 v[50:51], v[50:51], v[176:177] op_sel_hi:[1,0]
	v_pk_mul_f32 v[48:49], v[48:49], v[176:177] op_sel_hi:[1,0]
	v_pk_mul_f32 v[46:47], v[46:47], v[176:177] op_sel_hi:[1,0]
	v_pk_mul_f32 v[44:45], v[44:45], v[176:177] op_sel_hi:[1,0]
	v_pk_mul_f32 v[42:43], v[42:43], v[176:177] op_sel_hi:[1,0]
	v_pk_mul_f32 v[40:41], v[40:41], v[176:177] op_sel_hi:[1,0]
	v_pk_mul_f32 v[38:39], v[38:39], v[176:177] op_sel_hi:[1,0]
	v_pk_mul_f32 v[36:37], v[36:37], v[176:177] op_sel_hi:[1,0]
	v_pk_mul_f32 v[34:35], v[34:35], v[176:177] op_sel_hi:[1,0]
	v_pk_mul_f32 v[32:33], v[32:33], v[176:177] op_sel_hi:[1,0]
	v_pk_mul_f32 v[30:31], v[30:31], v[176:177] op_sel_hi:[1,0]
	v_pk_mul_f32 v[28:29], v[28:29], v[176:177] op_sel_hi:[1,0]
	v_pk_mul_f32 v[26:27], v[26:27], v[176:177] op_sel_hi:[1,0]
	v_pk_mul_f32 v[24:25], v[24:25], v[176:177] op_sel_hi:[1,0]
	v_pk_mul_f32 v[22:23], v[22:23], v[176:177] op_sel_hi:[1,0]
	v_pk_mul_f32 v[20:21], v[20:21], v[176:177] op_sel_hi:[1,0]
	v_pk_mul_f32 v[18:19], v[18:19], v[176:177] op_sel_hi:[1,0]
	v_pk_mul_f32 v[16:17], v[16:17], v[176:177] op_sel_hi:[1,0]
	v_pk_mul_f32 v[14:15], v[14:15], v[176:177] op_sel_hi:[1,0]
	v_pk_mul_f32 v[12:13], v[12:13], v[176:177] op_sel_hi:[1,0]
	v_pk_mul_f32 v[10:11], v[10:11], v[176:177] op_sel_hi:[1,0]
	v_pk_mul_f32 v[8:9], v[8:9], v[176:177] op_sel_hi:[1,0]
	v_pk_mul_f32 v[6:7], v[6:7], v[176:177] op_sel_hi:[1,0]
	v_pk_mul_f32 v[4:5], v[4:5], v[176:177] op_sel_hi:[1,0]
	v_pk_mul_f32 v[2:3], v[2:3], v[176:177] op_sel_hi:[1,0]
	v_pk_mul_f32 v[0:1], v[0:1], v[176:177] op_sel_hi:[1,0]
	v_mul_f32_e32 v164, v164, v176

.LBB0_611:
	s_mul_hi_u32 s6, s0, 0xaaaaaaab
	s_lshr_b32 s6, s6, 1
	s_mul_i32 s6, s6, 0x9000
	v_subrev_u32_e32 v64, s6, v201
	v_add_u32_e32 v216, s4, v209
	v_add_u32_e32 v212, v216, v64
	v_subrev_u32_e32 v213, s6, v206
	v_subrev_u32_e32 v214, s6, v207
	v_subrev_u32_e32 v215, s6, v208
	v_add_u32_e32 v213, v216, v213
	v_add_u32_e32 v214, v216, v214
	v_add_u32_e32 v215, v216, v215
	ds_read_b128 v[64:67], v212 offset:12288
	ds_read_b128 v[232:235], v213 offset:12288
	ds_read_b128 v[236:239], v214 offset:12288
	ds_read_b128 v[240:243], v215 offset:12288
	ds_read_b128 v[244:247], v212 offset:12416
	ds_read_b128 v[248:251], v213 offset:12416
	ds_read_b128 v[252:255], v214 offset:12416
	s_add_i32 s6, s5, 3
	v_readlane_b32 s7, v227, 15
	s_cmp_ge_u32 s6, s7
	s_cbranch_scc1 .Lmy_mla_nodma_b
	s_mul_hi_u32 s6, s1, 0xaaaaaaab
	s_lshr_b32 s6, s6, 1
	s_mul_i32 s6, s6, 0x9000
	s_sub_i32 s6, s4, s6
	v_readfirstlane_b32 s100, v202
	s_add_i32 s101, s36, 0x6000
	s_and_b32 s101, s101, 0x6000
	s_add_i32 s6, s6, s100
	s_add_i32 s101, s101, s100
	s_add_i32 m0, s6, 0x9000
	v_lshl_add_u64 v[216:217], v[166:167], 0, s[20:21]
	global_load_lds_dwordx4 v[172:173], off
	s_add_i32 m0, s6, 0xa000
	s_nop 0
	global_load_lds_dwordx4 v[170:171], off
	s_add_i32 m0, s6, 0xb000
	s_nop 0
	global_load_lds_dwordx4 v[168:169], off
	s_add_i32 m0, s101, 0x9000
	s_nop 0
	global_load_lds_dwordx4 v[166:167], off
	s_add_i32 m0, s101, 0xa000
	s_nop 0
	global_load_lds_dwordx4 v[216:217], off
.Lmy_mla_nodma_b:
	s_and_b32 s6, s36, 0x6000
	s_add_i32 s6, s6, 16
	s_waitcnt lgkmcnt(6)
	v_mfma_f32_32x32x16_bf16 v[64:79], v[64:67], v[142:145], 0
	v_max_f32_e32 v211, v80, v80
	v_max_f32_e32 v210, v81, v81
	v_max_f32_e32 v210, v211, v210
	v_max3_f32 v210, v210, v82, v83
	v_max3_f32 v210, v210, v84, v85
	v_max3_f32 v210, v210, v86, v87
	s_waitcnt lgkmcnt(5)
	v_mfma_f32_32x32x16_bf16 v[64:79], v[232:235], v[138:141], v[64:79]
	ds_read_b128 v[232:235], v215 offset:12416
	v_max3_f32 v210, v210, v88, v89
	v_max3_f32 v210, v210, v90, v91
	v_max3_f32 v210, v210, v92, v93
	v_max3_f32 v210, v210, v94, v95
	v_mov_b32_e32 v211, v210
	s_waitcnt lgkmcnt(5)
	v_mfma_f32_32x32x16_bf16 v[64:79], v[236:239], v[134:137], v[64:79]
	ds_read_b128 v[236:239], v212 offset:12544
	v_permlane32_swap_b32_e32 v210, v211
	v_max_f32_e32 v211, v211, v211
	v_max_f32_e32 v210, v210, v210
	v_max_f32_e32 v210, v210, v211
	v_add_f32_e32 v211, 0x41000000, v198
	v_cmp_gt_f32_e32 vcc, v210, v211
	s_cbranch_vccz .LBB0_613
	v_max_f32_e32 v210, v210, v210
	v_max_f32_e32 v211, v198, v198
	v_max_f32_e32 v210, v211, v210
	v_sub_f32_e32 v198, v198, v210
	v_exp_f32_e32 v198, v198
	s_nop 0
	v_pk_mul_f32 v[62:63], v[62:63], v[198:199] op_sel_hi:[1,0]
	v_pk_mul_f32 v[60:61], v[60:61], v[198:199] op_sel_hi:[1,0]
	v_pk_mul_f32 v[58:59], v[58:59], v[198:199] op_sel_hi:[1,0]
	v_pk_mul_f32 v[56:57], v[56:57], v[198:199] op_sel_hi:[1,0]
	v_pk_mul_f32 v[54:55], v[54:55], v[198:199] op_sel_hi:[1,0]
	v_pk_mul_f32 v[52:53], v[52:53], v[198:199] op_sel_hi:[1,0]
	v_pk_mul_f32 v[50:51], v[50:51], v[198:199] op_sel_hi:[1,0]
	v_pk_mul_f32 v[48:49], v[48:49], v[198:199] op_sel_hi:[1,0]
	v_pk_mul_f32 v[46:47], v[46:47], v[198:199] op_sel_hi:[1,0]
	v_pk_mul_f32 v[44:45], v[44:45], v[198:199] op_sel_hi:[1,0]
	v_pk_mul_f32 v[42:43], v[42:43], v[198:199] op_sel_hi:[1,0]
	v_pk_mul_f32 v[40:41], v[40:41], v[198:199] op_sel_hi:[1,0]
	v_pk_mul_f32 v[38:39], v[38:39], v[198:199] op_sel_hi:[1,0]
	v_pk_mul_f32 v[36:37], v[36:37], v[198:199] op_sel_hi:[1,0]
	v_pk_mul_f32 v[34:35], v[34:35], v[198:199] op_sel_hi:[1,0]
	v_pk_mul_f32 v[32:33], v[32:33], v[198:199] op_sel_hi:[1,0]
	v_pk_mul_f32 v[30:31], v[30:31], v[198:199] op_sel_hi:[1,0]
	v_pk_mul_f32 v[28:29], v[28:29], v[198:199] op_sel_hi:[1,0]
	v_pk_mul_f32 v[26:27], v[26:27], v[198:199] op_sel_hi:[1,0]
	v_pk_mul_f32 v[24:25], v[24:25], v[198:199] op_sel_hi:[1,0]
	v_pk_mul_f32 v[22:23], v[22:23], v[198:199] op_sel_hi:[1,0]
	v_pk_mul_f32 v[20:21], v[20:21], v[198:199] op_sel_hi:[1,0]
	v_pk_mul_f32 v[18:19], v[18:19], v[198:199] op_sel_hi:[1,0]
	v_pk_mul_f32 v[16:17], v[16:17], v[198:199] op_sel_hi:[1,0]
	v_pk_mul_f32 v[14:15], v[14:15], v[198:199] op_sel_hi:[1,0]
	v_pk_mul_f32 v[12:13], v[12:13], v[198:199] op_sel_hi:[1,0]
	v_pk_mul_f32 v[10:11], v[10:11], v[198:199] op_sel_hi:[1,0]
	v_pk_mul_f32 v[8:9], v[8:9], v[198:199] op_sel_hi:[1,0]
	v_pk_mul_f32 v[6:7], v[6:7], v[198:199] op_sel_hi:[1,0]
	v_pk_mul_f32 v[4:5], v[4:5], v[198:199] op_sel_hi:[1,0]
	v_pk_mul_f32 v[2:3], v[2:3], v[198:199] op_sel_hi:[1,0]
	v_pk_mul_f32 v[0:1], v[0:1], v[198:199] op_sel_hi:[1,0]
	v_mul_f32_e32 v177, v177, v198
	v_mov_b32_e32 v198, v210
